# grid barrier: agent-scope invalidate issued right after the arrival (the workgroup is parked in the barrier and only polls with L1-bypassing loads until the release), overlapping it with the wait
# baseline (speedup 1.0000x reference)
; DI void grid_barrier(unsigned* ctr, unsigned target) {
;   __syncthreads();
;   if (threadIdx.x == 0) {
;     __threadfence();
;     __hip_atomic_fetch_add(ctr, 1u, __ATOMIC_RELAXED, __HIP_MEMORY_SCOPE_AGENT);
;     unsigned spins = 0;
;     while (__hip_atomic_load(ctr, __ATOMIC_RELAXED, __HIP_MEMORY_SCOPE_AGENT) < target && spins < (1u << 26)) { __builtin_amdgcn_s_sleep(2); ++spins; }
;     __threadfence();
;   }
;   __syncthreads();
; }
.Lg3_nl:
.Lg3_w2:
	buffer_inv sc1
	v_readlane_b32 s11, v252, 12
	s_min_u32 s14, s33, 8
	s_mul_i32 s11, s11, s15
	s_add_u32 s11, s11, s14
.Lg3_lpb:
	global_load_dword v1, v131, s[22:23] offset:-1792 sc1
	s_add_u32 s10, s10, 1
	s_waitcnt vmcnt(0)
	v_cmp_gt_u32_e32 vcc, s11, v1
	s_cbranch_vccz .Lg3_okb
	s_cmp_lt_u32 s10, 0x100000
	s_cbranch_scc1 .Lg3_lpb
.Lg3_okb:
	s_branch .Lg3_fin
.Lg3_done:
	buffer_inv sc1
